# sel block loop: duplicated copy for full 16-entry lists with step-A vmcnt waits relaxed by the 16 prefetch loads and a drain moved to the end of step A
# speedup vs baseline: 1.0094x; 1.0094x over previous
; #define LAS __attribute__((address_space(3)))
; #define SEL_IDX(i) __shfl(myidx, (i) < last ? (i) : last)
; __device__ __forceinline__ void phase_sel(const Params& p, LAS unsigned char* lds, const bf16_t* Z, const float* G, const unsigned char* K8, const unsigned char* V8T, const float* ACC, const int* IDX, bf16_t* Mixed, int tid, int wid, int lane) {
;     ...
;         long qf[2];
;         { const u32x2 qa = bf8_to_fp8(qr0), qb2 = bf8_to_fp8(qr1); qf[0] = mk64(qa.x, qa.y); qf[1] = mk64(qb2.x, qb2.y); }
;         const int nblk = __builtin_popcountll(__ballot(myidx >= 0));
;         const int head = g * 4 + (cc & 3);
;         const float gate_pre = G[row * 32 + 8 + head * 3 + 1];
;         LAS unsigned char* land = lds + 32768 + wid * 4096;
; #pragma unroll
;         for (int d = 0; d < 4; ++d) __builtin_amdgcn_global_load_lds((const unsigned*)(ACC + row * 512 + head * 64 + 16 * d + 4 * q4), (LAS unsigned*)(land + d * 1024), 16, 0, 0);
;         float m = NEG, l = 0.f; f32x4 o[4];
; #pragma unroll
;         for (int d = 0; d < 4; ++d) o[d] = (f32x4){0.f, 0.f, 0.f, 0.f};
;         const unsigned char* Kb = K8 + (size_t)bg * SEQ * 64;
;         const unsigned char* Vb = V8T + (size_t)bg * SEQ * 64;
;         SelBuf b0, b1, b2, b3;
;         const int last = nblk - 1;
;     ...
;         int j0 = SEL_IDX(0), j1 = SEL_IDX(1), j2 = SEL_IDX(2), j3 = SEL_IDX(3);
;         sel_load_any(b0, Kb, Vb, lds, j0, cur, cc, q4); sel_load_any(b1, Kb, Vb, lds, j1, cur, cc, q4); sel_load_any(b2, Kb, Vb, lds, j2, cur, cc, q4); sel_load_any(b3, Kb, Vb, lds, j3, cur, cc, q4);
;         for (int k = 0; k < nblk; k += 4) {
.LBB0_646:
	s_waitcnt vmcnt(0)
	v_lshlrev_b32_e32 v0, 16, v110
	v_and_b32_e32 v110, 0xffff0000, v110
	v_cvt_pk_fp8_f32 v208, v0, v110
	v_lshlrev_b32_e32 v0, 16, v112
	v_and_b32_e32 v110, 0xffff0000, v112
	v_cvt_pk_fp8_f32 v209, v0, v110
	v_lshlrev_b32_e32 v0, 16, v113
	v_and_b32_e32 v110, 0xffff0000, v113
	v_cvt_pk_fp8_f32 v209, v0, v110 op_sel:[0,0,1]
	v_lshlrev_b32_e32 v0, 16, v98
	v_and_b32_e32 v98, 0xffff0000, v98
	v_cvt_pk_fp8_f32 v210, v0, v98
	v_lshlrev_b32_e32 v0, 16, v100
	v_and_b32_e32 v98, 0xffff0000, v100
	v_cvt_pk_fp8_f32 v211, v0, v98
	v_lshlrev_b32_e32 v140, 16, v111
	v_and_b32_e32 v111, 0xffff0000, v111
	v_lshlrev_b32_e32 v110, 16, v99
	v_and_b32_e32 v99, 0xffff0000, v99
	v_lshlrev_b32_e32 v0, 16, v101
	v_and_b32_e32 v98, 0xffff0000, v101
	v_cvt_pk_fp8_f32 v208, v140, v111 op_sel:[0,0,1]
	v_cvt_pk_fp8_f32 v210, v110, v99 op_sel:[0,0,1]
	v_cvt_pk_fp8_f32 v211, v0, v98 op_sel:[0,0,1]
	v_mov_b32_e32 v249, 0
	v_lshl_add_u64 v[212:213], v[138:139], 0, v[196:197]
	v_mov_b32_e32 v0, 0xf149f2ca
	s_mov_b32 s70, 0
	v_mov_b32_e32 v142, 0
	v_mov_b32_e32 v143, v249
	v_mov_b32_e32 v144, v249
	v_mov_b32_e32 v145, v249
	v_mov_b32_e32 v138, v249
	v_mov_b32_e32 v139, v249
	v_mov_b32_e32 v140, v249
	v_mov_b32_e32 v141, v249
	v_mov_b32_e32 v110, v249
	v_mov_b32_e32 v111, v249
	v_mov_b32_e32 v112, v249
	v_mov_b32_e32 v113, v249
	v_mov_b32_e32 v98, v249
	v_mov_b32_e32 v99, v249
	v_mov_b32_e32 v100, v249
	v_mov_b32_e32 v101, v249
	s_cmp_lt_u32 s51, 16
	s_cbranch_scc1 .LBB0_647
	s_cmp_lg_u32 s26, 16
	s_cbranch_scc1 .LBB0_647
	s_branch .Lsr_647

; __device__ __forceinline__ void sel_compute2(float& m, float& l, f32x4 (&o)[4], const long (&qf)[2], const SelBuf& A, const SelBuf& B, int kbA, int kbB, bool diagA, bool diagB, bool validB, int t, float c, int q4) {
;     f32x4 s[8];
; #pragma unroll
;     for (int ht = 0; ht < 4; ++ht) { f32x4 a = {0.f, 0.f, 0.f, 0.f}, bq = {0.f, 0.f, 0.f, 0.f};
;         a = __builtin_amdgcn_mfma_f32_16x16x32_fp8_fp8(A.k[ht].x, qf[0], a, 0, 0, 0);
;         bq = __builtin_amdgcn_mfma_f32_16x16x32_fp8_fp8(B.k[ht].x, qf[0], bq, 0, 0, 0);
;         a = __builtin_amdgcn_mfma_f32_16x16x32_fp8_fp8(A.k[ht].y, qf[1], a, 0, 0, 0);
;         bq = __builtin_amdgcn_mfma_f32_16x16x32_fp8_fp8(B.k[ht].y, qf[1], bq, 0, 0, 0);
;         s[ht] = a; s[4 + ht] = bq; }
;     if (diagA | diagB | !validB) {
; #pragma unroll
;         for (int ht = 0; ht < 4; ++ht)
; #pragma unroll
;             for (int e = 0; e < 4; ++e) { const int ko = 32 * (ht >> 1) + 8 * q4 + 4 * (ht & 1) + e;
;                 if (diagA && kbA + ko > t) s[ht][e] = NEG;
;                 if (!validB || (diagB && kbB + ko > t)) s[4 + ht][e] = NEG; }
;     }
; __device__ __forceinline__ void phase_sel(const Params& p, LAS unsigned char* lds, const bf16_t* Z, const float* G, const unsigned char* K8, const unsigned char* V8T, const float* ACC, const int* IDX, bf16_t* Mixed, int tid, int wid, int lane) {
;     ...
;             sel_compute2(m, l, o, qf, b0, b1, j0 * 64, j1 * 64, j0 == cur, j1 == cur, k + 1 < nblk, t, c, q4);
.Lsr_647:
	s_waitcnt vmcnt(23) lgkmcnt(7)
	v_mfma_f32_16x16x32_fp8_fp8 v[146:149], v[2:3], v[208:209], 0
	s_add_i32 s6, s70, 1
	s_cmp_ge_u32 s6, s26
	v_cmp_eq_u32_e64 s[4:5], s51, v198
	v_mfma_f32_16x16x32_fp8_fp8 v[170:173], v[4:5], v[210:211], v[146:149]
	v_cmp_eq_u32_e64 s[2:3], s51, v202
	s_cselect_b64 s[18:19], -1, 0
	s_cmp_lt_u32 s6, s26
	s_waitcnt vmcnt(22) lgkmcnt(6)
	v_mfma_f32_16x16x32_fp8_fp8 v[146:149], v[6:7], v[208:209], 0
	s_cselect_b64 s[8:9], -1, 0
	s_or_b64 s[6:7], s[2:3], s[4:5]
	s_or_b64 s[6:7], s[6:7], s[18:19]
	v_mfma_f32_16x16x32_fp8_fp8 v[154:157], v[42:43], v[208:209], 0
	v_mfma_f32_16x16x32_fp8_fp8 v[166:169], v[8:9], v[210:211], v[146:149]
	v_mfma_f32_16x16x32_fp8_fp8 v[146:149], v[44:45], v[210:211], v[154:157]
	s_waitcnt vmcnt(21) lgkmcnt(5)
	v_mfma_f32_16x16x32_fp8_fp8 v[154:157], v[10:11], v[208:209], 0
	v_mfma_f32_16x16x32_fp8_fp8 v[158:161], v[50:51], v[208:209], 0
	v_mfma_f32_16x16x32_fp8_fp8 v[150:153], v[34:35], v[208:209], 0
	v_mfma_f32_16x16x32_fp8_fp8 v[162:165], v[12:13], v[210:211], v[154:157]
	v_mfma_f32_16x16x32_fp8_fp8 v[154:157], v[52:53], v[210:211], v[158:161]
	s_waitcnt vmcnt(20) lgkmcnt(4)
	v_mfma_f32_16x16x32_fp8_fp8 v[158:161], v[14:15], v[208:209], 0
	v_mfma_f32_16x16x32_fp8_fp8 v[182:185], v[58:59], v[208:209], 0
	v_mfma_f32_16x16x32_fp8_fp8 v[150:153], v[36:37], v[210:211], v[150:153]
	v_mfma_f32_16x16x32_fp8_fp8 v[174:177], v[16:17], v[210:211], v[158:161]
	v_mfma_f32_16x16x32_fp8_fp8 v[158:161], v[60:61], v[210:211], v[182:185]
	s_and_saveexec_b64 s[16:17], s[6:7]
	s_cbranch_execz .Lsr_713
	v_lshlrev_b32_e32 v201, 6, v198
	s_nop 1
	v_or_b32_e32 v182, v201, v186
	v_cmp_lt_i32_e32 vcc, s50, v182
	s_and_b64 vcc, s[4:5], vcc
	v_cndmask_b32_e64 v182, 0, 1, s[8:9]
	v_lshlrev_b32_e32 v199, 6, v202
	v_cndmask_b32_e32 v170, v170, v180, vcc
	v_cmp_ne_u32_e64 s[6:7], 1, v182
	s_andn2_b64 vcc, exec, s[8:9]
	s_mov_b64 s[8:9], s[18:19]
	s_cbranch_vccnz .Lsr_650
	v_or_b32_e32 v182, v199, v186
	v_cmp_lt_i32_e32 vcc, s50, v182
	s_and_b64 s[8:9], s[2:3], vcc
	s_andn2_b64 s[20:21], s[18:19], exec
	s_and_b64 s[8:9], s[8:9], exec
	s_or_b64 s[8:9], s[20:21], s[8:9]

; __device__ __forceinline__ float ex2(float x) { return __builtin_amdgcn_exp2f(x); }
; __device__ __forceinline__ unsigned pk4_fp8(float a, float b, float c, float d) { int w = __builtin_amdgcn_cvt_pk_fp8_f32(a, b, 0, false); w = __builtin_amdgcn_cvt_pk_fp8_f32(c, d, w, true); return (unsigned)w; }
; #define SEL_IDX(i) __shfl(myidx, (i) < last ? (i) : last)
; __device__ __forceinline__ void sel_compute2(float& m, float& l, f32x4 (&o)[4], const long (&qf)[2], const SelBuf& A, const SelBuf& B, int kbA, int kbB, bool diagA, bool diagB, bool validB, int t, float c, int q4) {
;     ...
;     f32x2_t ps2 = {0.f, 0.f}; const f32x2_t c2 = {c, c}, mn2 = {mn, mn}, e8 = {8.f, 8.f};
; #pragma unroll
;     for (int ht = 0; ht < 8; ++ht)
; #pragma unroll
;         for (int e = 0; e < 4; e += 2) { f32x2_t tt = {s[ht][e], s[ht][e + 1]}; tt = (tt - mn2) * c2 + e8; s[ht][e] = ex2(tt.x); s[ht][e + 1] = ex2(tt.y); const f32x2_t pp = {s[ht][e], s[ht][e + 1]}; ps2 += pp; }
;     l = l * alpha + (ps2.x + ps2.y);
; #pragma unroll
;     for (int half = 0; half < 2; ++half) {
;         const long pa = mk64(pk4_fp8(s[2 * half][0], s[2 * half][1], s[2 * half][2], s[2 * half][3]), pk4_fp8(s[2 * half + 1][0], s[2 * half + 1][1], s[2 * half + 1][2], s[2 * half + 1][3]));
;         const long pbb = mk64(pk4_fp8(s[4 + 2 * half][0], s[4 + 2 * half][1], s[4 + 2 * half][2], s[4 + 2 * half][3]), pk4_fp8(s[4 + 2 * half + 1][0], s[4 + 2 * half + 1][1], s[4 + 2 * half + 1][2], s[4 + 2 * half + 1][3]));
; #pragma unroll
;         for (int d = 0; d < 4; ++d) {
;             o[d] = __builtin_amdgcn_mfma_f32_16x16x32_fp8_fp8(half ? A.v[d].y : A.v[d].x, pa, o[d], 0, 0, 0);
;             o[d] = __builtin_amdgcn_mfma_f32_16x16x32_fp8_fp8(half ? B.v[d].y : B.v[d].x, pbb, o[d], 0, 0, 0); }
;     }
; __device__ __forceinline__ void phase_sel(const Params& p, LAS unsigned char* lds, const bf16_t* Z, const float* G, const unsigned char* K8, const unsigned char* V8T, const float* ACC, const int* IDX, bf16_t* Mixed, int tid, int wid, int lane) {
;     ...
;         for (int k = 0; k < nblk; k += 4) {
;             sel_compute2(m, l, o, qf, b0, b1, j0 * 64, j1 * 64, j0 == cur, j1 == cur, k + 1 < nblk, t, c, q4);
;             if (k + 4 < nblk) { j0 = SEL_IDX(k + 4); j1 = SEL_IDX(k + 5); sel_load_any(b0, Kb, Vb, lds, j0, cur, cc, q4); sel_load_any(b1, Kb, Vb, lds, j1, cur, cc, q4); }
.Lsr_716:
	v_mov_b64_e32 v[182:183], s[64:65]
	v_fma_f32 v183, -v214, s62, v182
	v_pk_fma_f32 v[170:171], v[170:171], s[62:63], v[182:183] op_sel:[0,0,1] op_sel_hi:[1,0,1]
	v_pk_fma_f32 v[166:167], v[166:167], s[62:63], v[182:183] op_sel:[0,0,1] op_sel_hi:[1,0,1]
	v_exp_f32_e32 v170, v170
	v_exp_f32_e32 v171, v171
	v_exp_f32_e32 v166, v166
	v_exp_f32_e32 v167, v167
	v_pk_fma_f32 v[172:173], v[172:173], s[62:63], v[182:183] op_sel:[0,0,1] op_sel_hi:[1,0,1]
	v_pk_fma_f32 v[168:169], v[168:169], s[62:63], v[182:183] op_sel:[0,0,1] op_sel_hi:[1,0,1]
	v_pk_fma_f32 v[162:163], v[162:163], s[62:63], v[182:183] op_sel:[0,0,1] op_sel_hi:[1,0,1]
	v_pk_fma_f32 v[164:165], v[164:165], s[62:63], v[182:183] op_sel:[0,0,1] op_sel_hi:[1,0,1]
	v_pk_fma_f32 v[174:175], v[174:175], s[62:63], v[182:183] op_sel:[0,0,1] op_sel_hi:[1,0,1]
	v_pk_fma_f32 v[176:177], v[176:177], s[62:63], v[182:183] op_sel:[0,0,1] op_sel_hi:[1,0,1]
	v_pk_fma_f32 v[150:151], v[150:151], s[62:63], v[182:183] op_sel:[0,0,1] op_sel_hi:[1,0,1]
	v_pk_fma_f32 v[152:153], v[152:153], s[62:63], v[182:183] op_sel:[0,0,1] op_sel_hi:[1,0,1]
	v_pk_fma_f32 v[146:147], v[146:147], s[62:63], v[182:183] op_sel:[0,0,1] op_sel_hi:[1,0,1]
	v_pk_fma_f32 v[148:149], v[148:149], s[62:63], v[182:183] op_sel:[0,0,1] op_sel_hi:[1,0,1]
	v_pk_fma_f32 v[154:155], v[154:155], s[62:63], v[182:183] op_sel:[0,0,1] op_sel_hi:[1,0,1]
	v_pk_fma_f32 v[156:157], v[156:157], s[62:63], v[182:183] op_sel:[0,0,1] op_sel_hi:[1,0,1]
	v_pk_fma_f32 v[158:159], v[158:159], s[62:63], v[182:183] op_sel:[0,0,1] op_sel_hi:[1,0,1]
	v_pk_fma_f32 v[160:161], v[160:161], s[62:63], v[182:183] op_sel:[0,0,1] op_sel_hi:[1,0,1]
	v_exp_f32_e32 v172, v172
	v_exp_f32_e32 v173, v173
	v_exp_f32_e32 v168, v168
	v_exp_f32_e32 v169, v169
	v_exp_f32_e32 v150, v150
	v_exp_f32_e32 v151, v151
	v_exp_f32_e32 v146, v146
	v_exp_f32_e32 v147, v147
	v_cvt_pk_fp8_f32 v182, v170, v171
	v_cvt_pk_fp8_f32 v183, v166, v167
	v_exp_f32_e32 v152, v152
	v_exp_f32_e32 v153, v153
	v_exp_f32_e32 v148, v148
	v_exp_f32_e32 v149, v149
	v_cvt_pk_fp8_f32 v182, v172, v173 op_sel:[0,0,1]
	v_cvt_pk_fp8_f32 v183, v168, v169 op_sel:[0,0,1]
	v_cvt_pk_fp8_f32 v184, v150, v151
	v_cvt_pk_fp8_f32 v185, v146, v147
	v_exp_f32_e32 v162, v162
	v_exp_f32_e32 v163, v163
	v_exp_f32_e32 v174, v174
	v_exp_f32_e32 v175, v175
	v_cvt_pk_fp8_f32 v184, v152, v153 op_sel:[0,0,1]
	v_cvt_pk_fp8_f32 v185, v148, v149 op_sel:[0,0,1]
	s_waitcnt vmcnt(19)
	v_mfma_f32_16x16x32_fp8_fp8 v[142:145], v[18:19], v[182:183], v[142:145]
	v_exp_f32_e32 v164, v164
	v_exp_f32_e32 v165, v165
	v_exp_f32_e32 v176, v176
	s_waitcnt vmcnt(18)
	v_mfma_f32_16x16x32_fp8_fp8 v[138:141], v[26:27], v[182:183], v[138:141]
	v_exp_f32_e32 v177, v177
	v_exp_f32_e32 v154, v154
	v_exp_f32_e32 v155, v155
	s_waitcnt vmcnt(17)
	v_mfma_f32_16x16x32_fp8_fp8 v[110:113], v[30:31], v[182:183], v[110:113]
	v_exp_f32_e32 v158, v158
	v_exp_f32_e32 v159, v159
	v_exp_f32_e32 v156, v156
	s_waitcnt vmcnt(16)
	v_mfma_f32_16x16x32_fp8_fp8 v[98:101], v[22:23], v[182:183], v[98:101]
	v_cvt_pk_fp8_f32 v182, v162, v163
	v_cvt_pk_fp8_f32 v183, v174, v175
	v_mfma_f32_16x16x32_fp8_fp8 v[142:145], v[66:67], v[184:185], v[142:145]
	v_exp_f32_e32 v157, v157
	v_exp_f32_e32 v160, v160
	v_exp_f32_e32 v161, v161
	v_mfma_f32_16x16x32_fp8_fp8 v[138:141], v[78:79], v[184:185], v[138:141]
	v_cvt_pk_fp8_f32 v182, v164, v165 op_sel:[0,0,1]
	v_cvt_pk_fp8_f32 v183, v176, v177 op_sel:[0,0,1]
	s_add_i32 s71, s70, 4
	v_mfma_f32_16x16x32_fp8_fp8 v[110:113], v[90:91], v[184:185], v[110:113]
	s_cmp_ge_u32 s71, s26
	s_cselect_b64 s[16:17], -1, 0
	s_and_b64 vcc, exec, s[16:17]
	v_mfma_f32_16x16x32_fp8_fp8 v[98:101], v[86:87], v[184:185], v[98:101]
	v_cvt_pk_fp8_f32 v184, v154, v155
	v_cvt_pk_fp8_f32 v185, v158, v159
	v_mfma_f32_16x16x32_fp8_fp8 v[142:145], v[20:21], v[182:183], v[142:145]
	v_cvt_pk_fp8_f32 v184, v156, v157 op_sel:[0,0,1]
	v_cvt_pk_fp8_f32 v185, v160, v161 op_sel:[0,0,1]
	v_mfma_f32_16x16x32_fp8_fp8 v[138:141], v[28:29], v[182:183], v[138:141]
	v_mfma_f32_16x16x32_fp8_fp8 v[110:113], v[32:33], v[182:183], v[110:113]
	v_mfma_f32_16x16x32_fp8_fp8 v[98:101], v[24:25], v[182:183], v[98:101]
	v_mfma_f32_16x16x32_fp8_fp8 v[142:145], v[68:69], v[184:185], v[142:145]
	v_mfma_f32_16x16x32_fp8_fp8 v[138:141], v[80:81], v[184:185], v[138:141]
	v_mfma_f32_16x16x32_fp8_fp8 v[110:113], v[92:93], v[184:185], v[110:113]
	v_mfma_f32_16x16x32_fp8_fp8 v[98:101], v[88:89], v[184:185], v[98:101]
	s_waitcnt vmcnt(0)
	s_cbranch_vccnz .Lsr_726
	v_and_or_b32 v2, s71, 60, v181
	v_lshlrev_b32_e32 v2, 2, v2
	ds_bpermute_b32 v198, v2, v246
	s_add_i32 s2, s70, 5
	s_min_i32 s2, s2, s69
	v_and_or_b32 v2, s2, 63, v181
	v_lshlrev_b32_e32 v2, 2, v2
	ds_bpermute_b32 v202, v2, v246
	s_waitcnt lgkmcnt(1)
	v_cmp_eq_u32_e32 vcc, s51, v198
	s_nop 1
	v_cndmask_b32_e64 v2, -1, 2, vcc
	v_cmp_ne_u32_e32 vcc, s68, v198
	s_nop 1
	v_cndmask_b32_e32 v2, 1, v2, vcc
	v_cmp_ne_u32_e32 vcc, 0, v198
	s_nop 1
	v_cndmask_b32_e32 v34, 0, v2, vcc
	v_cmp_lt_i32_e32 vcc, -1, v34
	s_and_saveexec_b64 s[2:3], vcc
	s_xor_b64 s[2:3], exec, s[2:3]
	s_cbranch_execz .Lsr_719
	v_lshlrev_b32_e32 v2, 13, v34
	v_add3_u32 v18, 0, v2, v194
	v_add_u32_e32 v14, v18, v217
	v_add_u32_e32 v22, v18, v196
	ds_read_b128 v[2:5], v14
	ds_read_b128 v[6:9], v14 offset:256
	ds_read_b128 v[10:13], v14 offset:2048
	ds_read_b128 v[14:17], v14 offset:2304
	ds_read_b128 v[18:21], v22 offset:4096
	ds_read_b128 v[26:29], v22 offset:5120
	ds_read_b128 v[30:33], v22 offset:6144
	ds_read_b128 v[22:25], v22 offset:7168
